# mix phase static priority: filler items at s_setprio 1, diff-latent attention waves at 0 (reset to 0 at phase exit)
# speedup vs baseline: 1.0279x; 1.0198x over previous
.Lmix_dispatch:
	s_setprio 1
	s_cmpk_gt_i32 s40, 0xff
	s_cbranch_scc0 .LBB0_261
	s_cmpk_gt_u32 s40, 0x1ff
	s_cbranch_scc0 .LBB0_262
	s_cmpk_gt_u32 s40, 0x2ff
	s_cbranch_scc0 .LBB0_263
	s_cmpk_gt_u32 s40, 0x3ff
	s_cbranch_scc0 .LBB0_264
	s_cmpk_gt_u32 s40, 0x5ff
	s_cbranch_scc0 .LBB0_265
	s_cmpk_gt_u32 s40, 0x7ff
	s_cbranch_scc0 .LBB0_266
	s_cmpk_gt_u32 s40, 0x9ff
	s_cbranch_scc0 .LBB0_267
	s_cmpk_gt_u32 s40, 0xaff
	s_mov_b64 s[2:3], -1
	s_cbranch_scc0 .LBB0_268
	v_readlane_b32 s12, v252, 2
	v_readlane_b32 s72, v253, 51
	v_readlane_b32 s18, v252, 8
	v_readlane_b32 s20, v252, 10
	v_readlane_b32 s21, v252, 11
	v_readlane_b32 s76, v253, 55
	v_readlane_b32 s77, v253, 56
	s_lshl_b32 s6, s40, 2
	s_mov_b32 s7, -4
	v_readlane_b32 s16, v252, 6
	v_readlane_b32 s17, v252, 7
	s_mov_b64 s[20:21], s[76:77]
	s_movk_i32 s18, 0x104
	v_readlane_b32 s13, v252, 3
	v_readlane_b32 s14, v252, 4
	v_readlane_b32 s15, v252, 5
	v_readlane_b32 s19, v252, 9
	v_readlane_b32 s22, v252, 12
	v_readlane_b32 s23, v252, 13
	v_readlane_b32 s24, v252, 14
	v_readlane_b32 s25, v252, 15
	v_readlane_b32 s26, v252, 16
	v_readlane_b32 s27, v252, 17
	v_readlane_b32 s73, v253, 52
	v_readlane_b32 s74, v253, 53
	v_readlane_b32 s75, v253, 54
	v_readlane_b32 s78, v253, 57
	v_readlane_b32 s79, v253, 58
	v_readlane_b32 s80, v253, 59
	v_readlane_b32 s81, v253, 60
	v_readlane_b32 s82, v253, 61
	v_readlane_b32 s83, v253, 62
	v_readlane_b32 s84, v253, 63
	v_readlane_b32 s85, v254, 0
	v_readlane_b32 s86, v254, 1
	v_readlane_b32 s87, v254, 2

.LBB0_427:
	s_setprio 0
	s_bitcmp1_b32 s18, 0
	s_cselect_b32 s98, 0x4800, 0
	v_or_b32_e32 v210, s98, v166
	v_add_u32_e32 v210, v210, v171
	ds_read_b128 v[4:7], v210
	ds_read_b128 v[8:11], v210 offset:32
	s_cmpk_gt_u32 s18, 0x41
	s_cbranch_scc1 .LBB0_431
	s_mov_b64 s[8:9], 0x100
	s_cmp_lt_u32 s18, 2
	s_mov_b64 s[4:5], s[0:1]
	s_mov_b64 s[6:7], s[2:3]
	s_cbranch_scc1 .LBB0_430
	s_lshl_b64 s[4:5], s[56:57], 7
	s_add_u32 s6, s15, s4
	s_addc_u32 s7, s16, s5
	s_lshl_b64 s[4:5], s[56:57], 1
	s_add_u32 s4, s13, s4
	s_addc_u32 s5, s14, s5
	s_mov_b64 s[8:9], 0x1000

.LBB0_440:
	s_setprio 0
	s_mov_b64 s[0:1], 0
	s_movk_i32 s61, 0x3fff
